# FFN-in epilogue: non-temporal hint on the activation stores (keeps the normalized input resident for the later N tiles)
# speedup vs baseline: 1.0064x; 1.0064x over previous
.LBB0_681:
	v_lshl_add_u32 v164, s6, 8, v155
	s_lshr_b32 s1, s6, 5
	v_ashrrev_i32_e32 v165, 31, v164
	s_mul_i32 s28, s1, 0x1600
	v_lshl_add_u64 v[166:167], v[164:165], 2, s[10:11]
	s_ashr_i32 s29, s28, 31
	global_load_dword v165, v[166:167], off
	global_load_dword v241, v[166:167], off offset:64
	global_load_dword v242, v[166:167], off offset:128
	global_load_dword v243, v[166:167], off offset:192
	global_load_dword v244, v[166:167], off offset:512
	global_load_dword v245, v[166:167], off offset:576
	global_load_dword v246, v[166:167], off offset:640
	global_load_dword v247, v[166:167], off offset:704
	s_lshl_b64 s[28:29], s[28:29], 2
	s_add_u32 s1, s48, s28
	s_addc_u32 s21, s49, s29
	s_lshl_b32 s28, s0, 8
	s_ashr_i32 s29, s28, 31
	s_lshl_b64 s[28:29], s[28:29], 2
	s_add_u32 s1, s1, s28
	s_addc_u32 s6, s21, s29
	s_lshl_b32 s21, s50, 2
	s_add_u32 s28, s1, s21
	s_addc_u32 s29, s6, 0
	v_lshlrev_b32_e32 v96, 2, v154
	global_load_dwordx4 v[108:111], v96, s[28:29]
	global_load_dwordx4 v[104:107], v96, s[28:29] offset:512
	global_load_dwordx4 v[100:103], v96, s[28:29] offset:16
	s_nop 0
	global_load_dwordx4 v[96:99], v96, s[28:29] offset:528
	v_mov_b64_e32 v[168:169], s[12:13]
	s_lshl_b32 s0, s0, 7
	v_mad_i64_i32 v[176:177], s[28:29], v164, s57, v[168:169]
	s_ashr_i32 s1, s0, 31
	s_lshl_b64 s[28:29], s[0:1], 1
	s_lshl_b32 s6, s50, 1
	v_lshl_add_u64 v[176:177], v[176:177], 0, s[28:29]
	v_lshlrev_b32_e32 v152, 1, v154
	v_or_b32_e32 v178, 16, v164
	v_lshl_add_u64 v[176:177], v[176:177], 0, s[6:7]
	v_ashrrev_i32_e32 v179, 31, v178
	v_lshl_add_u64 v[176:177], v[176:177], 0, v[152:153]
	v_lshl_add_u64 v[180:181], v[178:179], 2, s[10:11]
	s_waitcnt vmcnt(0)
	v_fmamk_f32 v165, v165, 0x3a800000, v174
	v_mul_f32_e32 v175, 0x4b800000, v165
	v_cmp_gt_f32_e32 vcc, s58, v165
	s_nop 1
	v_cndmask_b32_e32 v165, v165, v175, vcc
	v_rsq_f32_e32 v165, v165
	s_nop 0
	v_mul_f32_e32 v175, 0x45800000, v165
	v_cndmask_b32_e32 v182, v165, v175, vcc
	v_pk_fma_f32 v[140:141], v[140:141], v[182:183], v[108:109] op_sel_hi:[1,0,1]
	v_pk_fma_f32 v[142:143], v[142:143], v[182:183], v[110:111] op_sel_hi:[1,0,1]
	v_pk_fma_f32 v[134:135], v[134:135], v[182:183], v[106:107] op_sel_hi:[1,0,1]
	v_pk_fma_f32 v[132:133], v[132:133], v[182:183], v[104:105] op_sel_hi:[1,0,1]
	v_pk_fma_f32 v[136:137], v[136:137], v[182:183], v[100:101] op_sel_hi:[1,0,1]
	v_pk_fma_f32 v[138:139], v[138:139], v[182:183], v[102:103] op_sel_hi:[1,0,1]
	v_pk_fma_f32 v[130:131], v[130:131], v[182:183], v[98:99] op_sel_hi:[1,0,1]
	v_pk_fma_f32 v[128:129], v[128:129], v[182:183], v[96:97] op_sel_hi:[1,0,1]
	v_pk_mul_f32 v[182:183], v[142:143], s[18:19] op_sel_hi:[1,0]
	v_pk_mul_f32 v[184:185], v[140:141], s[18:19] op_sel_hi:[1,0]
	v_pk_mul_f32 v[132:133], v[140:141], v[132:133]
	v_pk_mul_f32 v[134:135], v[142:143], v[134:135]
	v_pk_mul_f32 v[140:141], v[138:139], s[18:19] op_sel_hi:[1,0]
	v_pk_mul_f32 v[142:143], v[136:137], s[18:19] op_sel_hi:[1,0]
	v_pk_mul_f32 v[128:129], v[136:137], v[128:129]
	v_pk_mul_f32 v[130:131], v[138:139], v[130:131]
	v_exp_f32_e32 v136, v184
	v_exp_f32_e32 v137, v185
	v_exp_f32_e32 v138, v182
	v_exp_f32_e32 v139, v183
	v_exp_f32_e32 v142, v142
	v_exp_f32_e32 v140, v140
	v_exp_f32_e32 v141, v141
	v_exp_f32_e32 v143, v143
	v_pk_add_f32 v[138:139], v[138:139], 1.0 op_sel_hi:[1,0]
	v_pk_add_f32 v[136:137], v[136:137], 1.0 op_sel_hi:[1,0]
	v_pk_add_f32 v[140:141], v[140:141], 1.0 op_sel_hi:[1,0]
	v_pk_add_f32 v[142:143], v[142:143], 1.0 op_sel_hi:[1,0]
	v_rcp_f32_e32 v136, v136
	v_rcp_f32_e32 v137, v137
	v_rcp_f32_e32 v138, v138
	v_rcp_f32_e32 v139, v139
	v_rcp_f32_e32 v142, v142
	v_rcp_f32_e32 v140, v140
	v_rcp_f32_e32 v141, v141
	v_rcp_f32_e32 v143, v143
	v_pk_mul_f32 v[134:135], v[134:135], v[138:139]
	v_pk_mul_f32 v[132:133], v[132:133], v[136:137]
	v_pk_mul_f32 v[136:137], v[130:131], v[140:141]
	v_pk_mul_f32 v[130:131], v[128:129], v[142:143]
	v_cvt_pk_bf16_f32 v128, v132, v133
	v_cvt_pk_bf16_f32 v129, v134, v135
	v_cvt_pk_bf16_f32 v130, v130, v131
	v_cvt_pk_bf16_f32 v131, v136, v137
	global_store_dwordx4 v[176:177], v[128:131], off nt
	s_nop 0
	s_nop 0
	v_or_b32_e32 v128, 32, v164
	v_ashrrev_i32_e32 v129, 31, v128
	v_lshl_add_u64 v[132:133], v[128:129], 2, s[10:11]
	v_mad_i64_i32 v[130:131], s[0:1], v178, s57, v[168:169]
	v_lshl_add_u64 v[130:131], v[130:131], 0, s[28:29]
	v_lshl_add_u64 v[130:131], v[130:131], 0, s[6:7]
	v_lshl_add_u64 v[130:131], v[130:131], 0, v[152:153]
	v_fmamk_f32 v129, v241, 0x3a800000, v174
	v_mul_f32_e32 v134, 0x4b800000, v129
	v_cmp_gt_f32_e32 vcc, s58, v129
	s_nop 1
	v_cndmask_b32_e32 v129, v129, v134, vcc
	v_rsq_f32_e32 v129, v129
	s_nop 0
	v_mul_f32_e32 v134, 0x45800000, v129
	v_cndmask_b32_e32 v134, v129, v134, vcc
	v_pk_fma_f32 v[124:125], v[124:125], v[134:135], v[108:109] op_sel_hi:[1,0,1]
	v_pk_fma_f32 v[126:127], v[126:127], v[134:135], v[110:111] op_sel_hi:[1,0,1]
	v_pk_fma_f32 v[118:119], v[118:119], v[134:135], v[106:107] op_sel_hi:[1,0,1]
	v_pk_fma_f32 v[116:117], v[116:117], v[134:135], v[104:105] op_sel_hi:[1,0,1]
	v_pk_fma_f32 v[120:121], v[120:121], v[134:135], v[100:101] op_sel_hi:[1,0,1]
	v_pk_fma_f32 v[122:123], v[122:123], v[134:135], v[102:103] op_sel_hi:[1,0,1]
	v_pk_fma_f32 v[114:115], v[114:115], v[134:135], v[98:99] op_sel_hi:[1,0,1]
	v_pk_fma_f32 v[112:113], v[112:113], v[134:135], v[96:97] op_sel_hi:[1,0,1]
	v_pk_mul_f32 v[134:135], v[126:127], s[18:19] op_sel_hi:[1,0]
	v_pk_mul_f32 v[136:137], v[124:125], s[18:19] op_sel_hi:[1,0]
	v_pk_mul_f32 v[116:117], v[124:125], v[116:117]
	v_pk_mul_f32 v[118:119], v[126:127], v[118:119]
	v_pk_mul_f32 v[124:125], v[122:123], s[18:19] op_sel_hi:[1,0]
	v_pk_mul_f32 v[126:127], v[120:121], s[18:19] op_sel_hi:[1,0]
	v_pk_mul_f32 v[112:113], v[120:121], v[112:113]
	v_pk_mul_f32 v[114:115], v[122:123], v[114:115]
	v_exp_f32_e32 v120, v136
	v_exp_f32_e32 v121, v137
	v_exp_f32_e32 v122, v134
	v_exp_f32_e32 v123, v135
	v_exp_f32_e32 v126, v126
	v_exp_f32_e32 v124, v124
	v_exp_f32_e32 v125, v125
	v_exp_f32_e32 v127, v127
	v_pk_add_f32 v[122:123], v[122:123], 1.0 op_sel_hi:[1,0]
	v_pk_add_f32 v[120:121], v[120:121], 1.0 op_sel_hi:[1,0]
	v_pk_add_f32 v[124:125], v[124:125], 1.0 op_sel_hi:[1,0]
	v_pk_add_f32 v[126:127], v[126:127], 1.0 op_sel_hi:[1,0]
	v_rcp_f32_e32 v120, v120
	v_rcp_f32_e32 v121, v121
	v_rcp_f32_e32 v122, v122
	v_rcp_f32_e32 v123, v123
	v_rcp_f32_e32 v126, v126
	v_rcp_f32_e32 v124, v124
	v_rcp_f32_e32 v125, v125
	v_rcp_f32_e32 v127, v127
	v_pk_mul_f32 v[118:119], v[118:119], v[122:123]
	v_pk_mul_f32 v[116:117], v[116:117], v[120:121]
	v_pk_mul_f32 v[120:121], v[114:115], v[124:125]
	v_pk_mul_f32 v[114:115], v[112:113], v[126:127]
	v_cvt_pk_bf16_f32 v112, v116, v117
	v_cvt_pk_bf16_f32 v113, v118, v119
	v_cvt_pk_bf16_f32 v114, v114, v115
	v_cvt_pk_bf16_f32 v115, v120, v121
	global_store_dwordx4 v[130:131], v[112:115], off nt
	s_nop 0
	s_nop 0
	v_or_b32_e32 v112, 48, v164
	v_ashrrev_i32_e32 v113, 31, v112
	v_lshl_add_u64 v[116:117], v[112:113], 2, s[10:11]
	v_mad_i64_i32 v[114:115], s[0:1], v128, s57, v[168:169]
	v_lshl_add_u64 v[114:115], v[114:115], 0, s[28:29]
	v_lshl_add_u64 v[114:115], v[114:115], 0, s[6:7]
	v_lshl_add_u64 v[114:115], v[114:115], 0, v[152:153]
	v_fmamk_f32 v113, v242, 0x3a800000, v174
	v_mul_f32_e32 v118, 0x4b800000, v113
	v_cmp_gt_f32_e32 vcc, s58, v113
	s_nop 1
	v_cndmask_b32_e32 v113, v113, v118, vcc
	v_rsq_f32_e32 v113, v113
	s_nop 0
	v_mul_f32_e32 v118, 0x45800000, v113
	v_cndmask_b32_e32 v118, v113, v118, vcc
	v_pk_fma_f32 v[92:93], v[92:93], v[118:119], v[108:109] op_sel_hi:[1,0,1]
	v_pk_fma_f32 v[94:95], v[94:95], v[118:119], v[110:111] op_sel_hi:[1,0,1]
	v_pk_fma_f32 v[86:87], v[86:87], v[118:119], v[106:107] op_sel_hi:[1,0,1]
	v_pk_fma_f32 v[84:85], v[84:85], v[118:119], v[104:105] op_sel_hi:[1,0,1]
	v_pk_fma_f32 v[88:89], v[88:89], v[118:119], v[100:101] op_sel_hi:[1,0,1]
	v_pk_fma_f32 v[90:91], v[90:91], v[118:119], v[102:103] op_sel_hi:[1,0,1]
	v_pk_fma_f32 v[82:83], v[82:83], v[118:119], v[98:99] op_sel_hi:[1,0,1]
	v_pk_fma_f32 v[80:81], v[80:81], v[118:119], v[96:97] op_sel_hi:[1,0,1]
	v_pk_mul_f32 v[118:119], v[94:95], s[18:19] op_sel_hi:[1,0]
	v_pk_mul_f32 v[120:121], v[92:93], s[18:19] op_sel_hi:[1,0]
	v_pk_mul_f32 v[84:85], v[92:93], v[84:85]
	v_pk_mul_f32 v[86:87], v[94:95], v[86:87]
	v_pk_mul_f32 v[92:93], v[90:91], s[18:19] op_sel_hi:[1,0]
	v_pk_mul_f32 v[94:95], v[88:89], s[18:19] op_sel_hi:[1,0]
	v_pk_mul_f32 v[80:81], v[88:89], v[80:81]
	v_pk_mul_f32 v[82:83], v[90:91], v[82:83]
	v_exp_f32_e32 v88, v120
	v_exp_f32_e32 v89, v121
	v_exp_f32_e32 v90, v118
	v_exp_f32_e32 v91, v119
	v_exp_f32_e32 v94, v94
	v_exp_f32_e32 v92, v92
	v_exp_f32_e32 v93, v93
	v_exp_f32_e32 v95, v95
	v_pk_add_f32 v[90:91], v[90:91], 1.0 op_sel_hi:[1,0]
	v_pk_add_f32 v[88:89], v[88:89], 1.0 op_sel_hi:[1,0]
	v_pk_add_f32 v[92:93], v[92:93], 1.0 op_sel_hi:[1,0]
	v_pk_add_f32 v[94:95], v[94:95], 1.0 op_sel_hi:[1,0]
	v_rcp_f32_e32 v88, v88
	v_rcp_f32_e32 v89, v89
	v_rcp_f32_e32 v90, v90
	v_rcp_f32_e32 v91, v91
	v_rcp_f32_e32 v94, v94
	v_rcp_f32_e32 v92, v92
	v_rcp_f32_e32 v93, v93
	v_rcp_f32_e32 v95, v95
	v_pk_mul_f32 v[86:87], v[86:87], v[90:91]
	v_pk_mul_f32 v[84:85], v[84:85], v[88:89]
	v_pk_mul_f32 v[88:89], v[82:83], v[92:93]
	v_pk_mul_f32 v[82:83], v[80:81], v[94:95]
	v_cvt_pk_bf16_f32 v80, v84, v85
	v_cvt_pk_bf16_f32 v81, v86, v87
	v_cvt_pk_bf16_f32 v82, v82, v83
	v_cvt_pk_bf16_f32 v83, v88, v89
	global_store_dwordx4 v[114:115], v[80:83], off nt
	s_nop 0
	s_nop 0
	v_mad_i64_i32 v[80:81], s[0:1], v112, s57, v[168:169]
	v_lshl_add_u64 v[80:81], v[80:81], 0, s[28:29]
	v_lshl_add_u64 v[80:81], v[80:81], 0, s[6:7]
	v_lshl_add_u64 v[80:81], v[80:81], 0, v[152:153]
	v_fmamk_f32 v82, v243, 0x3a800000, v174
	v_mul_f32_e32 v83, 0x4b800000, v82
	v_cmp_gt_f32_e32 vcc, s58, v82
	s_nop 1
	v_cndmask_b32_e32 v82, v82, v83, vcc
	v_rsq_f32_e32 v82, v82
	s_nop 0
	v_mul_f32_e32 v83, 0x45800000, v82
	v_cndmask_b32_e32 v82, v82, v83, vcc
	v_pk_fma_f32 v[76:77], v[76:77], v[82:83], v[108:109] op_sel_hi:[1,0,1]
	v_pk_fma_f32 v[78:79], v[78:79], v[82:83], v[110:111] op_sel_hi:[1,0,1]
	v_pk_fma_f32 v[70:71], v[70:71], v[82:83], v[106:107] op_sel_hi:[1,0,1]
	v_pk_fma_f32 v[68:69], v[68:69], v[82:83], v[104:105] op_sel_hi:[1,0,1]
	v_pk_fma_f32 v[72:73], v[72:73], v[82:83], v[100:101] op_sel_hi:[1,0,1]
	v_pk_fma_f32 v[74:75], v[74:75], v[82:83], v[102:103] op_sel_hi:[1,0,1]
	v_pk_fma_f32 v[66:67], v[66:67], v[82:83], v[98:99] op_sel_hi:[1,0,1]
	v_pk_fma_f32 v[64:65], v[64:65], v[82:83], v[96:97] op_sel_hi:[1,0,1]
	v_pk_mul_f32 v[82:83], v[78:79], s[18:19] op_sel_hi:[1,0]
	v_pk_mul_f32 v[84:85], v[76:77], s[18:19] op_sel_hi:[1,0]
	v_pk_mul_f32 v[68:69], v[76:77], v[68:69]
	v_pk_mul_f32 v[70:71], v[78:79], v[70:71]
	v_pk_mul_f32 v[76:77], v[74:75], s[18:19] op_sel_hi:[1,0]
	v_pk_mul_f32 v[78:79], v[72:73], s[18:19] op_sel_hi:[1,0]
	v_pk_mul_f32 v[64:65], v[72:73], v[64:65]
	v_pk_mul_f32 v[66:67], v[74:75], v[66:67]
	v_exp_f32_e32 v72, v84
	v_exp_f32_e32 v73, v85
	v_exp_f32_e32 v74, v82
	v_exp_f32_e32 v75, v83
	v_exp_f32_e32 v78, v78
	v_exp_f32_e32 v76, v76
	v_exp_f32_e32 v77, v77
	v_exp_f32_e32 v79, v79
	v_pk_add_f32 v[74:75], v[74:75], 1.0 op_sel_hi:[1,0]
	v_pk_add_f32 v[72:73], v[72:73], 1.0 op_sel_hi:[1,0]
	v_pk_add_f32 v[76:77], v[76:77], 1.0 op_sel_hi:[1,0]
	v_pk_add_f32 v[78:79], v[78:79], 1.0 op_sel_hi:[1,0]
	v_rcp_f32_e32 v72, v72
	v_rcp_f32_e32 v73, v73
	v_rcp_f32_e32 v74, v74
	v_rcp_f32_e32 v75, v75
	v_rcp_f32_e32 v78, v78
	v_rcp_f32_e32 v76, v76
	v_rcp_f32_e32 v77, v77
	v_rcp_f32_e32 v79, v79
	v_pk_mul_f32 v[70:71], v[70:71], v[74:75]
	v_pk_mul_f32 v[68:69], v[68:69], v[72:73]
	v_pk_mul_f32 v[72:73], v[66:67], v[76:77]
	v_pk_mul_f32 v[66:67], v[64:65], v[78:79]
	v_cvt_pk_bf16_f32 v64, v68, v69
	v_cvt_pk_bf16_f32 v65, v70, v71
	v_cvt_pk_bf16_f32 v66, v66, v67
	v_cvt_pk_bf16_f32 v67, v72, v73
	global_store_dwordx4 v[80:81], v[64:67], off nt
	s_nop 0
	s_nop 0
	v_add_u32_e32 v64, 0x80, v164
	v_mad_i64_i32 v[64:65], s[0:1], v64, s57, v[168:169]
	v_lshl_add_u64 v[64:65], v[64:65], 0, s[28:29]
	v_lshl_add_u64 v[64:65], v[64:65], 0, s[6:7]
	v_lshl_add_u64 v[64:65], v[64:65], 0, v[152:153]
	v_fmamk_f32 v66, v244, 0x3a800000, v174
	v_mul_f32_e32 v67, 0x4b800000, v66
	v_cmp_gt_f32_e32 vcc, s58, v66
	s_nop 1
	v_cndmask_b32_e32 v66, v66, v67, vcc
	v_rsq_f32_e32 v66, v66
	s_nop 0
	v_mul_f32_e32 v67, 0x45800000, v66
	v_cndmask_b32_e32 v66, v66, v67, vcc
	v_pk_fma_f32 v[60:61], v[60:61], v[66:67], v[108:109] op_sel_hi:[1,0,1]
	v_pk_fma_f32 v[62:63], v[62:63], v[66:67], v[110:111] op_sel_hi:[1,0,1]
	v_pk_fma_f32 v[54:55], v[54:55], v[66:67], v[106:107] op_sel_hi:[1,0,1]
	v_pk_fma_f32 v[52:53], v[52:53], v[66:67], v[104:105] op_sel_hi:[1,0,1]
	v_pk_fma_f32 v[56:57], v[56:57], v[66:67], v[100:101] op_sel_hi:[1,0,1]
	v_pk_fma_f32 v[58:59], v[58:59], v[66:67], v[102:103] op_sel_hi:[1,0,1]
	v_pk_fma_f32 v[50:51], v[50:51], v[66:67], v[98:99] op_sel_hi:[1,0,1]
	v_pk_fma_f32 v[48:49], v[48:49], v[66:67], v[96:97] op_sel_hi:[1,0,1]
	v_pk_mul_f32 v[66:67], v[62:63], s[18:19] op_sel_hi:[1,0]
	v_pk_mul_f32 v[68:69], v[60:61], s[18:19] op_sel_hi:[1,0]
	v_pk_mul_f32 v[52:53], v[60:61], v[52:53]
	v_pk_mul_f32 v[54:55], v[62:63], v[54:55]
	v_pk_mul_f32 v[60:61], v[58:59], s[18:19] op_sel_hi:[1,0]
	v_pk_mul_f32 v[62:63], v[56:57], s[18:19] op_sel_hi:[1,0]
	v_pk_mul_f32 v[48:49], v[56:57], v[48:49]
	v_pk_mul_f32 v[50:51], v[58:59], v[50:51]
	v_exp_f32_e32 v56, v68
	v_exp_f32_e32 v57, v69
	v_exp_f32_e32 v58, v66
	v_exp_f32_e32 v59, v67
	v_exp_f32_e32 v62, v62
	v_exp_f32_e32 v60, v60
	v_exp_f32_e32 v61, v61
	v_exp_f32_e32 v63, v63
	v_pk_add_f32 v[58:59], v[58:59], 1.0 op_sel_hi:[1,0]
	v_pk_add_f32 v[56:57], v[56:57], 1.0 op_sel_hi:[1,0]
	v_pk_add_f32 v[60:61], v[60:61], 1.0 op_sel_hi:[1,0]
	v_pk_add_f32 v[62:63], v[62:63], 1.0 op_sel_hi:[1,0]
	v_rcp_f32_e32 v56, v56
	v_rcp_f32_e32 v57, v57
	v_rcp_f32_e32 v58, v58
	v_rcp_f32_e32 v59, v59
	v_rcp_f32_e32 v62, v62
	v_rcp_f32_e32 v60, v60
	v_rcp_f32_e32 v61, v61
	v_rcp_f32_e32 v63, v63
	v_pk_mul_f32 v[54:55], v[54:55], v[58:59]
	v_pk_mul_f32 v[52:53], v[52:53], v[56:57]
	v_pk_mul_f32 v[56:57], v[50:51], v[60:61]
	v_pk_mul_f32 v[50:51], v[48:49], v[62:63]
	v_cvt_pk_bf16_f32 v48, v52, v53
	v_cvt_pk_bf16_f32 v49, v54, v55
	v_cvt_pk_bf16_f32 v50, v50, v51
	v_cvt_pk_bf16_f32 v51, v56, v57
	global_store_dwordx4 v[64:65], v[48:51], off nt
	s_nop 0
	s_nop 0
	v_add_u32_e32 v48, 0x90, v164
	v_mad_i64_i32 v[48:49], s[0:1], v48, s57, v[168:169]
	v_lshl_add_u64 v[48:49], v[48:49], 0, s[28:29]
	v_lshl_add_u64 v[48:49], v[48:49], 0, s[6:7]
	v_lshl_add_u64 v[48:49], v[48:49], 0, v[152:153]
	v_fmamk_f32 v50, v245, 0x3a800000, v174
	v_mul_f32_e32 v51, 0x4b800000, v50
	v_cmp_gt_f32_e32 vcc, s58, v50
	s_nop 1
	v_cndmask_b32_e32 v50, v50, v51, vcc
	v_rsq_f32_e32 v50, v50
	s_nop 0
	v_mul_f32_e32 v51, 0x45800000, v50
	v_cndmask_b32_e32 v50, v50, v51, vcc
	v_pk_fma_f32 v[44:45], v[44:45], v[50:51], v[108:109] op_sel_hi:[1,0,1]
	v_pk_fma_f32 v[46:47], v[46:47], v[50:51], v[110:111] op_sel_hi:[1,0,1]
	v_pk_fma_f32 v[38:39], v[38:39], v[50:51], v[106:107] op_sel_hi:[1,0,1]
	v_pk_fma_f32 v[36:37], v[36:37], v[50:51], v[104:105] op_sel_hi:[1,0,1]
	v_pk_fma_f32 v[40:41], v[40:41], v[50:51], v[100:101] op_sel_hi:[1,0,1]
	v_pk_fma_f32 v[42:43], v[42:43], v[50:51], v[102:103] op_sel_hi:[1,0,1]
	v_pk_fma_f32 v[34:35], v[34:35], v[50:51], v[98:99] op_sel_hi:[1,0,1]
	v_pk_fma_f32 v[32:33], v[32:33], v[50:51], v[96:97] op_sel_hi:[1,0,1]
	v_pk_mul_f32 v[50:51], v[46:47], s[18:19] op_sel_hi:[1,0]
	v_pk_mul_f32 v[52:53], v[44:45], s[18:19] op_sel_hi:[1,0]
	v_pk_mul_f32 v[36:37], v[44:45], v[36:37]
	v_pk_mul_f32 v[38:39], v[46:47], v[38:39]
	v_pk_mul_f32 v[44:45], v[42:43], s[18:19] op_sel_hi:[1,0]
	v_pk_mul_f32 v[46:47], v[40:41], s[18:19] op_sel_hi:[1,0]
	v_pk_mul_f32 v[32:33], v[40:41], v[32:33]
	v_pk_mul_f32 v[34:35], v[42:43], v[34:35]
	v_exp_f32_e32 v40, v52
	v_exp_f32_e32 v41, v53
	v_exp_f32_e32 v42, v50
	v_exp_f32_e32 v43, v51
	v_exp_f32_e32 v46, v46
	v_exp_f32_e32 v44, v44
	v_exp_f32_e32 v45, v45
	v_exp_f32_e32 v47, v47
	v_pk_add_f32 v[42:43], v[42:43], 1.0 op_sel_hi:[1,0]
	v_pk_add_f32 v[40:41], v[40:41], 1.0 op_sel_hi:[1,0]
	v_pk_add_f32 v[44:45], v[44:45], 1.0 op_sel_hi:[1,0]
	v_pk_add_f32 v[46:47], v[46:47], 1.0 op_sel_hi:[1,0]
	v_rcp_f32_e32 v40, v40
	v_rcp_f32_e32 v41, v41
	v_rcp_f32_e32 v42, v42
	v_rcp_f32_e32 v43, v43
	v_rcp_f32_e32 v46, v46
	v_rcp_f32_e32 v44, v44
	v_rcp_f32_e32 v45, v45
	v_rcp_f32_e32 v47, v47
	v_pk_mul_f32 v[38:39], v[38:39], v[42:43]
	v_pk_mul_f32 v[36:37], v[36:37], v[40:41]
	v_pk_mul_f32 v[40:41], v[34:35], v[44:45]
	v_pk_mul_f32 v[34:35], v[32:33], v[46:47]
	v_cvt_pk_bf16_f32 v32, v36, v37
	v_cvt_pk_bf16_f32 v33, v38, v39
	v_cvt_pk_bf16_f32 v34, v34, v35
	v_cvt_pk_bf16_f32 v35, v40, v41
	global_store_dwordx4 v[48:49], v[32:35], off nt
	s_nop 0
	s_nop 0
	v_add_u32_e32 v32, 0xa0, v164
	v_mad_i64_i32 v[32:33], s[0:1], v32, s57, v[168:169]
	v_lshl_add_u64 v[32:33], v[32:33], 0, s[28:29]
	v_lshl_add_u64 v[32:33], v[32:33], 0, s[6:7]
	v_lshl_add_u64 v[32:33], v[32:33], 0, v[152:153]
	v_fmamk_f32 v34, v246, 0x3a800000, v174
	v_mul_f32_e32 v35, 0x4b800000, v34
	v_cmp_gt_f32_e32 vcc, s58, v34
	s_nop 1
	v_cndmask_b32_e32 v34, v34, v35, vcc
	v_rsq_f32_e32 v34, v34
	s_nop 0
	v_mul_f32_e32 v35, 0x45800000, v34
	v_cndmask_b32_e32 v34, v34, v35, vcc
	v_pk_fma_f32 v[28:29], v[28:29], v[34:35], v[108:109] op_sel_hi:[1,0,1]
	v_pk_fma_f32 v[30:31], v[30:31], v[34:35], v[110:111] op_sel_hi:[1,0,1]
	v_pk_fma_f32 v[22:23], v[22:23], v[34:35], v[106:107] op_sel_hi:[1,0,1]
	v_pk_fma_f32 v[20:21], v[20:21], v[34:35], v[104:105] op_sel_hi:[1,0,1]
	v_pk_fma_f32 v[24:25], v[24:25], v[34:35], v[100:101] op_sel_hi:[1,0,1]
	v_pk_fma_f32 v[26:27], v[26:27], v[34:35], v[102:103] op_sel_hi:[1,0,1]
	v_pk_fma_f32 v[18:19], v[18:19], v[34:35], v[98:99] op_sel_hi:[1,0,1]
	v_pk_fma_f32 v[16:17], v[16:17], v[34:35], v[96:97] op_sel_hi:[1,0,1]
	v_pk_mul_f32 v[34:35], v[30:31], s[18:19] op_sel_hi:[1,0]
	v_pk_mul_f32 v[36:37], v[28:29], s[18:19] op_sel_hi:[1,0]
	v_pk_mul_f32 v[20:21], v[28:29], v[20:21]
	v_pk_mul_f32 v[22:23], v[30:31], v[22:23]
	v_pk_mul_f32 v[28:29], v[26:27], s[18:19] op_sel_hi:[1,0]
	v_pk_mul_f32 v[30:31], v[24:25], s[18:19] op_sel_hi:[1,0]
	v_pk_mul_f32 v[16:17], v[24:25], v[16:17]
	v_pk_mul_f32 v[18:19], v[26:27], v[18:19]
	v_exp_f32_e32 v24, v36
	v_exp_f32_e32 v25, v37
	v_exp_f32_e32 v26, v34
	v_exp_f32_e32 v27, v35
	v_exp_f32_e32 v30, v30
	v_exp_f32_e32 v28, v28
	v_exp_f32_e32 v29, v29
	v_exp_f32_e32 v31, v31
	v_pk_add_f32 v[26:27], v[26:27], 1.0 op_sel_hi:[1,0]
	v_pk_add_f32 v[24:25], v[24:25], 1.0 op_sel_hi:[1,0]
	v_pk_add_f32 v[28:29], v[28:29], 1.0 op_sel_hi:[1,0]
	v_pk_add_f32 v[30:31], v[30:31], 1.0 op_sel_hi:[1,0]
	v_rcp_f32_e32 v24, v24
	v_rcp_f32_e32 v25, v25
	v_rcp_f32_e32 v26, v26
	v_rcp_f32_e32 v27, v27
	v_rcp_f32_e32 v30, v30
	v_rcp_f32_e32 v28, v28
	v_rcp_f32_e32 v29, v29
	v_rcp_f32_e32 v31, v31
	v_pk_mul_f32 v[22:23], v[22:23], v[26:27]
	v_pk_mul_f32 v[20:21], v[20:21], v[24:25]
	v_pk_mul_f32 v[24:25], v[18:19], v[28:29]
	v_pk_mul_f32 v[18:19], v[16:17], v[30:31]
	v_cvt_pk_bf16_f32 v16, v20, v21
	v_cvt_pk_bf16_f32 v17, v22, v23
	v_cvt_pk_bf16_f32 v18, v18, v19
	v_cvt_pk_bf16_f32 v19, v24, v25
	global_store_dwordx4 v[32:33], v[16:19], off nt
	s_nop 0
	s_andn2_b64 vcc, exec, s[2:3]
	v_add_u32_e32 v16, 0xb0, v164
	v_mad_i64_i32 v[16:17], s[0:1], v16, s57, v[168:169]
	v_lshl_add_u64 v[16:17], v[16:17], 0, s[28:29]
	v_lshl_add_u64 v[16:17], v[16:17], 0, s[6:7]
	v_lshl_add_u64 v[16:17], v[16:17], 0, v[152:153]
	v_fmamk_f32 v18, v247, 0x3a800000, v174
	v_mul_f32_e32 v19, 0x4b800000, v18
	v_cmp_gt_f32_e64 s[2:3], s58, v18
	s_nop 1
	v_cndmask_b32_e64 v18, v18, v19, s[2:3]
	v_rsq_f32_e32 v18, v18
	s_nop 0
	v_mul_f32_e32 v19, 0x45800000, v18
	v_cndmask_b32_e64 v18, v18, v19, s[2:3]
	v_pk_fma_f32 v[12:13], v[12:13], v[18:19], v[108:109] op_sel_hi:[1,0,1]
	v_pk_fma_f32 v[14:15], v[14:15], v[18:19], v[110:111] op_sel_hi:[1,0,1]
	v_pk_fma_f32 v[6:7], v[6:7], v[18:19], v[106:107] op_sel_hi:[1,0,1]
	v_pk_fma_f32 v[4:5], v[4:5], v[18:19], v[104:105] op_sel_hi:[1,0,1]
	v_pk_fma_f32 v[8:9], v[8:9], v[18:19], v[100:101] op_sel_hi:[1,0,1]
	v_pk_fma_f32 v[10:11], v[10:11], v[18:19], v[102:103] op_sel_hi:[1,0,1]
	v_pk_fma_f32 v[2:3], v[2:3], v[18:19], v[98:99] op_sel_hi:[1,0,1]
	v_pk_fma_f32 v[0:1], v[0:1], v[18:19], v[96:97] op_sel_hi:[1,0,1]
	v_pk_mul_f32 v[18:19], v[14:15], s[18:19] op_sel_hi:[1,0]
	v_pk_mul_f32 v[20:21], v[12:13], s[18:19] op_sel_hi:[1,0]
	v_pk_mul_f32 v[4:5], v[12:13], v[4:5]
	v_pk_mul_f32 v[6:7], v[14:15], v[6:7]
	v_pk_mul_f32 v[12:13], v[10:11], s[18:19] op_sel_hi:[1,0]
	v_pk_mul_f32 v[14:15], v[8:9], s[18:19] op_sel_hi:[1,0]
	v_pk_mul_f32 v[0:1], v[8:9], v[0:1]
	v_pk_mul_f32 v[2:3], v[10:11], v[2:3]
	v_exp_f32_e32 v8, v20
	v_exp_f32_e32 v9, v21
	v_exp_f32_e32 v10, v18
	v_exp_f32_e32 v11, v19
	v_exp_f32_e32 v14, v14
	v_exp_f32_e32 v12, v12
	v_exp_f32_e32 v13, v13
	v_exp_f32_e32 v15, v15
	v_pk_add_f32 v[10:11], v[10:11], 1.0 op_sel_hi:[1,0]
	v_pk_add_f32 v[8:9], v[8:9], 1.0 op_sel_hi:[1,0]
	v_pk_add_f32 v[12:13], v[12:13], 1.0 op_sel_hi:[1,0]
	v_pk_add_f32 v[14:15], v[14:15], 1.0 op_sel_hi:[1,0]
	v_rcp_f32_e32 v8, v8
	v_rcp_f32_e32 v9, v9
	v_rcp_f32_e32 v10, v10
	v_rcp_f32_e32 v11, v11
	v_rcp_f32_e32 v14, v14
	v_rcp_f32_e32 v12, v12
	v_rcp_f32_e32 v13, v13
	v_rcp_f32_e32 v15, v15
	v_pk_mul_f32 v[6:7], v[6:7], v[10:11]
	v_pk_mul_f32 v[4:5], v[4:5], v[8:9]
	v_pk_mul_f32 v[8:9], v[2:3], v[12:13]
	v_pk_mul_f32 v[2:3], v[0:1], v[14:15]
	v_cvt_pk_bf16_f32 v0, v4, v5
	v_cvt_pk_bf16_f32 v1, v6, v7
	v_cvt_pk_bf16_f32 v2, v2, v3
	v_cvt_pk_bf16_f32 v3, v8, v9
	s_mov_b64 s[2:3], -1
	global_store_dwordx4 v[16:17], v[0:3], off nt
	s_cbranch_vccnz .LBB0_674
	s_andn2_b64 vcc, exec, s[8:9]
	s_cbranch_vccnz .LBB0_673
	s_barrier
	s_branch .LBB0_673
